# grid barrier flat release: non-leader blocks poll the global generation flag directly instead of the XCD-local forwarded flag
# speedup vs baseline: 1.0014x; 1.0014x over previous
; DEV unsigned xb_ld(unsigned* p) { return __hip_atomic_load(p, __ATOMIC_RELAXED, __HIP_MEMORY_SCOPE_AGENT); }
; DEV unsigned xb_add(unsigned* p, unsigned v) { return __hip_atomic_fetch_add(p, v, __ATOMIC_RELAXED, __HIP_MEMORY_SCOPE_AGENT); }
; #define XB_SPIN(cond, bar) do { unsigned _sp = 0; while (cond) { __builtin_amdgcn_s_sleep(1); \
;     if ((++_sp & 255u) == 0u) { if (xb_ld(&(bar)[XB_TMO])) break; if (_sp > XB_SPIN_CAP) { atomicAdd(&(bar)[XB_TMO], 1u); break; } } } } while (0)
; DEV void xcd_barrier(const XcdBarrier& b) {
;     ...
;     const unsigned old = xb_add(&bar[XB_XSUB(b.x)], 1u);
;     const unsigned gen = old / nloc;
;     if (old + 1u == (gen + 1u) * nloc) {
;       __builtin_amdgcn_fence(__ATOMIC_RELEASE, "agent");
;       asm volatile("s_waitcnt vmcnt(0)" ::: "memory");
;       const unsigned og = xb_add(&bar[XB_TOP], 1u);
;       const unsigned tg = og / nx;
;       if (og + 1u == (tg + 1u) * nx) xb_add(&bar[XB_TOPGEN], 1u);
;       else XB_SPIN(xb_ld(&bar[XB_TOPGEN]) == tg, bar);
;       __builtin_amdgcn_fence(__ATOMIC_ACQUIRE, "agent");
;       xb_add(&bar[XB_XGEN(b.x)], 1u);
;       asm volatile("s_waitcnt vmcnt(0)" ::: "memory");
;     } else {
;       XB_SPIN(xb_ld(&bar[XB_XGEN(b.x)]) == gen, bar);
;       __builtin_amdgcn_fence(__ATOMIC_ACQUIRE, "agent");
;       asm volatile("s_waitcnt vmcnt(0)" ::: "memory");
;     }
.LBB0_98:
	s_or_b64 exec, exec, s[2:3]
	v_cvt_f32_u32_e32 v5, v3
	s_waitcnt vmcnt(0)
	v_readfirstlane_b32 s2, v4
	v_sub_u32_e32 v4, 0, v3
	v_rcp_iflag_f32_e32 v5, v5
	v_add_u32_e32 v6, s2, v0
	v_mul_f32_e32 v5, 0x4f7ffffe, v5
	v_cvt_u32_f32_e32 v5, v5
	v_mul_lo_u32 v0, v4, v5
	v_mul_hi_u32 v0, v5, v0
	v_add_u32_e32 v0, v5, v0
	v_mul_hi_u32 v0, v6, v0
	v_mul_lo_u32 v4, v0, v3
	v_sub_u32_e32 v4, v6, v4
	v_add_u32_e32 v5, 1, v0
	v_cmp_ge_u32_e32 vcc, v4, v3
	s_nop 1
	v_cndmask_b32_e32 v0, v0, v5, vcc
	v_sub_u32_e32 v5, v4, v3
	v_cndmask_b32_e32 v4, v4, v5, vcc
	v_add_u32_e32 v5, 1, v0
	v_cmp_ge_u32_e32 vcc, v4, v3
	v_add_u32_e32 v4, 1, v6
	s_nop 0
	v_cndmask_b32_e32 v0, v0, v5, vcc
	v_mul_lo_u32 v5, v3, v0
	v_add_u32_e32 v3, v5, v3
	v_cmp_ne_u32_e32 vcc, v4, v3
	s_and_saveexec_b64 s[2:3], vcc
	s_xor_b64 s[2:3], exec, s[2:3]
	s_cbranch_execz .LBB0_112
	v_readlane_b32 s6, v252, 40
	v_readlane_b32 s7, v252, 41
	s_waitcnt lgkmcnt(0)
	s_nop 3
	global_load_dword v2, v1, s[6:7] sc1
	s_waitcnt vmcnt(0)
	v_cmp_eq_u32_e32 vcc, v2, v0
	s_and_saveexec_b64 s[6:7], vcc
	s_cbranch_execz .LBB0_111
	s_mov_b32 s18, 1
	s_mov_b64 s[8:9], 0
	s_branch .LBB0_102
